# attention QK and PV MFMA sections: K/V fragment LDS reads issued ahead in a register ring instead of read-wait-mfma
# speedup vs baseline: 1.0142x; 1.0066x over previous
; #define MFMA16(a, b, c) __builtin_amdgcn_mfma_f32_16x16x32_bf16(a, b, c, 0, 0, 0)
; __device__ __forceinline__ void attn_phase(const Params& p, int l, bf16_t* PROJ, LAS unsigned char* L) {
;     ...
;             f32x4 s[4];
; #pragma unroll
;             for (int nt = 0; nt < 4; ++nt) { s[nt] = (f32x4){0.f, 0.f, 0.f, 0.f};
; #pragma unroll
;                 for (int ks = 0; ks < 4; ++ks) s[nt] = MFMA16(aq[ks], LDFRAG(Ks + hh * (64 * 136), nt * 16 + fr, 136, ks * 32 + fq * 8), s[nt]); }
;             if (j <= 3) {
;                 const float cb = relb[hh * 320 + 319];
; #pragma unroll
;                 for (int nt = 0; nt < 4; ++nt) s[nt] += cb;
;             } else {
;                 const int dbase = (8 - j) * 64 + rt * 16 + fq * 4 - fr;
; #pragma unroll
;                 for (int nt = 0; nt < 4; ++nt)
; #pragma unroll
;                     for (int jj = 0; jj < 4; ++jj) { int dist = dbase + jj - nt * 16; dist = dist > 256 ? 256 : dist; s[nt][jj] += relb[hh * 320 + dist + 63]; }
.LBB0_350:
	s_waitcnt lgkmcnt(0)
	s_barrier
	ds_read_b128 v[80:83], v198
	ds_read_b128 v[128:131], v198 offset:64
	ds_read_b128 v[132:135], v198 offset:128
	ds_read_b128 v[140:143], v198 offset:192
	ds_read_b128 v[84:87], v198 offset:4352
	ds_read_b128 v[144:147], v198 offset:4416
	ds_read_b128 v[222:225], v198 offset:4480
	ds_read_b128 v[226:229], v198 offset:4544
	ds_read_b128 v[88:91], v198 offset:8704
	ds_read_b128 v[230:233], v198 offset:8768
	ds_read_b128 v[234:237], v198 offset:8832
	ds_read_b128 v[238:241], v198 offset:8896
	ds_read_b128 v[92:95], v198 offset:13056
	ds_read_b128 v[242:245], v198 offset:13120
	ds_read_b128 v[246:249], v198 offset:13184
	s_waitcnt lgkmcnt(14)
	v_mfma_f32_16x16x32_bf16 v[80:83], v[0:3], v[80:83], 0
	s_waitcnt lgkmcnt(13)
	v_mfma_f32_16x16x32_bf16 v[80:83], v[4:7], v[128:131], v[80:83]
	ds_read_b128 v[128:131], v198 offset:13248
	s_waitcnt lgkmcnt(13)
	v_mfma_f32_16x16x32_bf16 v[80:83], v[8:11], v[132:135], v[80:83]
	s_waitcnt lgkmcnt(12)
	v_mfma_f32_16x16x32_bf16 v[80:83], v[12:15], v[140:143], v[80:83]
	s_waitcnt lgkmcnt(11)
	v_mfma_f32_16x16x32_bf16 v[84:87], v[0:3], v[84:87], 0
	s_waitcnt lgkmcnt(10)
	v_mfma_f32_16x16x32_bf16 v[84:87], v[4:7], v[144:147], v[84:87]
	s_waitcnt lgkmcnt(9)
	v_mfma_f32_16x16x32_bf16 v[84:87], v[8:11], v[222:225], v[84:87]
	s_waitcnt lgkmcnt(8)
	v_mfma_f32_16x16x32_bf16 v[84:87], v[12:15], v[226:229], v[84:87]
	s_waitcnt lgkmcnt(7)
	v_mfma_f32_16x16x32_bf16 v[88:91], v[0:3], v[88:91], 0
	s_waitcnt lgkmcnt(6)
	v_mfma_f32_16x16x32_bf16 v[88:91], v[4:7], v[230:233], v[88:91]
	s_waitcnt lgkmcnt(5)
	v_mfma_f32_16x16x32_bf16 v[88:91], v[8:11], v[234:237], v[88:91]
	s_waitcnt lgkmcnt(4)
	v_mfma_f32_16x16x32_bf16 v[88:91], v[12:15], v[238:241], v[88:91]
	s_waitcnt lgkmcnt(3)
	v_mfma_f32_16x16x32_bf16 v[92:95], v[0:3], v[92:95], 0
	s_waitcnt lgkmcnt(2)
	v_mfma_f32_16x16x32_bf16 v[92:95], v[4:7], v[242:245], v[92:95]
	s_waitcnt lgkmcnt(1)
	v_mfma_f32_16x16x32_bf16 v[92:95], v[8:11], v[246:249], v[92:95]
	s_waitcnt lgkmcnt(0)
	v_mfma_f32_16x16x32_bf16 v[92:95], v[12:15], v[128:131], v[92:95]
	s_mov_b64 s[20:21], -1
	s_cmp_gt_i32 s3, 3
	s_cbranch_scc0 .LBB0_352
	v_add_u32_e32 v128, 48, v113
	v_min_i32_e32 v129, 0x100, v128
	v_min_i32_e32 v130, 0xff, v128
	v_min_i32_e32 v131, 0xfe, v128
	v_min_i32_e32 v128, 0xfd, v128
	v_lshl_add_u32 v132, v128, 2, v159
	v_add_u32_e32 v128, 32, v113
	v_min_i32_e32 v133, 0x100, v128
	v_min_i32_e32 v134, 0xff, v128
	v_lshl_add_u32 v129, v129, 2, v159
	v_lshl_add_u32 v130, v130, 2, v159
	v_lshl_add_u32 v131, v131, 2, v159
	v_lshl_add_u32 v133, v133, 2, v159
	v_lshl_add_u32 v134, v134, 2, v159
	v_min_i32_e32 v135, 0xfe, v128
	v_min_i32_e32 v128, 0xfd, v128
	v_lshl_add_u32 v135, v135, 2, v159
	v_lshl_add_u32 v138, v128, 2, v159
	ds_read_b32 v128, v129 offset:252
	ds_read_b32 v129, v130 offset:256
	ds_read_b32 v130, v131 offset:260
	ds_read_b32 v131, v132 offset:264
	ds_read_b32 v144, v133 offset:252
	ds_read_b32 v145, v134 offset:256
	ds_read_b32 v132, v135 offset:260
	ds_read_b32 v133, v138 offset:264
	v_add_u32_e32 v134, 16, v113
	v_min_i32_e32 v135, 0x100, v134
	v_lshl_add_u32 v135, v135, 2, v159
	v_min_i32_e32 v138, 0xff, v134
	v_min_i32_e32 v139, 0xfe, v134
	v_min_i32_e32 v134, 0xfd, v134
	v_min_i32_e32 v140, 0x100, v113
	v_min_i32_e32 v141, 0xff, v113
	v_min_i32_e32 v142, 0xfe, v113
	v_min_i32_e32 v143, 0xfd, v113
	v_lshl_add_u32 v138, v138, 2, v159
	v_lshl_add_u32 v139, v139, 2, v159
	v_lshl_add_u32 v134, v134, 2, v159
	v_lshl_add_u32 v140, v140, 2, v159
	v_lshl_add_u32 v141, v141, 2, v159
	v_lshl_add_u32 v142, v142, 2, v159
	v_lshl_add_u32 v143, v143, 2, v159
	ds_read_b32 v146, v135 offset:252
	ds_read_b32 v147, v138 offset:256
	ds_read_b32 v148, v139 offset:260
	ds_read_b32 v149, v134 offset:264
	ds_read_b32 v222, v140 offset:252
	ds_read_b32 v223, v141 offset:256
	ds_read_b32 v224, v142 offset:260
	ds_read_b32 v225, v143 offset:264
	s_waitcnt lgkmcnt(12)
	v_pk_add_f32 v[134:135], v[82:83], v[130:131]
	v_pk_add_f32 v[142:143], v[80:81], v[128:129]
	s_waitcnt lgkmcnt(8)
	v_pk_add_f32 v[132:133], v[86:87], v[132:133]
	v_pk_add_f32 v[144:145], v[84:85], v[144:145]
	s_waitcnt lgkmcnt(4)
	v_pk_add_f32 v[130:131], v[90:91], v[148:149]
	v_pk_add_f32 v[146:147], v[88:89], v[146:147]
	s_waitcnt lgkmcnt(0)
	v_pk_add_f32 v[128:129], v[94:95], v[224:225]
	v_pk_add_f32 v[148:149], v[92:93], v[222:223]
	s_mov_b64 s[20:21], 0

; __device__ __forceinline__ void attn_phase(const Params& p, int l, bf16_t* PROJ, LAS unsigned char* L) {
;     ...
; #pragma unroll
;             for (int jj = 0; jj < 4; ++jj) {
;                 float tm = fmaxf(fmaxf(s[0][jj], s[1][jj]), fmaxf(s[2][jj], s[3][jj]));
;                 tm = fmaxf(tm, __shfl_xor(tm, 1)); tm = fmaxf(tm, __shfl_xor(tm, 2)); tm = fmaxf(tm, __shfl_xor(tm, 4)); tm = fmaxf(tm, __shfl_xor(tm, 8));
;                 const float mn = fmaxf(mrow[jj], tm), alpha = __builtin_amdgcn_exp2f(mrow[jj] - mn); mrow[jj] = mn;
;                 float rsum = 0.f;
; #pragma unroll
;                 for (int nt = 0; nt < 4; ++nt) { const float pv = __builtin_amdgcn_exp2f(s[nt][jj] - mn); s[nt][jj] = pv; rsum += pv; }
;                 lsum[jj] = lsum[jj] * alpha + rsum;
; #pragma unroll
;                 for (int e = 0; e < 8; ++e) O[e][jj] *= alpha;
;             }
.LBB0_354:
	v_max_f32_e32 v80, v148, v148
	v_max_f32_e32 v81, v146, v146
	v_max_f32_e32 v80, v81, v80
	v_max3_f32 v80, v142, v144, v80
	v_max_f32_e32 v82, v147, v147
	v_max_f32_e32 v92, v131, v131
	s_add_i32 s20, s3, 1
	s_add_i32 s22, s22, 64
	s_waitcnt lgkmcnt(0)
	s_nop 1
	v_max_f32_dpp v80, v80, v80 quad_perm:[1,0,3,2] row_mask:0xf bank_mask:0xf
	v_subrev_u32_e32 v113, 64, v113
	s_cmp_gt_i32 s3, 7
	s_waitcnt lgkmcnt(0)
	s_nop 1
	v_max_f32_dpp v80, v80, v80 quad_perm:[2,3,0,1] row_mask:0xf bank_mask:0xf
	s_waitcnt lgkmcnt(0)
	s_nop 1
	v_max_f32_dpp v80, v80, v80 row_half_mirror row_mask:0xf bank_mask:0xf
	s_nop 1
	v_mov_b32_dpp v81, v80 row_mirror row_mask:0xf bank_mask:0xf
	s_waitcnt lgkmcnt(0)
	v_max3_f32 v221, v220, v80, v81
	v_sub_f32_e32 v80, v220, v221
	v_exp_f32_e32 v89, v80
	v_max_f32_e32 v80, v149, v149
	v_max_f32_e32 v80, v82, v80
	v_max3_f32 v80, v143, v145, v80
	v_sub_f32_e32 v81, v142, v221
	v_exp_f32_e32 v87, v81
	v_sub_f32_e32 v81, v144, v221
	v_exp_f32_e32 v85, v81
	s_waitcnt lgkmcnt(0)
	s_nop 1
	v_max_f32_dpp v80, v80, v80 quad_perm:[1,0,3,2] row_mask:0xf bank_mask:0xf
	v_sub_f32_e32 v81, v146, v221
	v_exp_f32_e32 v83, v81
	v_sub_f32_e32 v81, v148, v221
	v_exp_f32_e32 v81, v81
	s_waitcnt lgkmcnt(0)
	s_nop 1
	v_max_f32_dpp v80, v80, v80 quad_perm:[2,3,0,1] row_mask:0xf bank_mask:0xf
	s_waitcnt lgkmcnt(0)
	s_nop 1
	v_max_f32_dpp v80, v80, v80 row_half_mirror row_mask:0xf bank_mask:0xf
	s_nop 1
	v_mov_b32_dpp v82, v80 row_mirror row_mask:0xf bank_mask:0xf
	s_waitcnt lgkmcnt(0)
	v_max3_f32 v144, v219, v80, v82
	v_sub_f32_e32 v80, v143, v144
	v_exp_f32_e32 v86, v80
	v_sub_f32_e32 v80, v145, v144
	v_exp_f32_e32 v84, v80
	v_sub_f32_e32 v80, v147, v144
	v_exp_f32_e32 v82, v80
	v_sub_f32_e32 v80, v149, v144
	v_sub_f32_e32 v88, v219, v144
	v_exp_f32_e32 v80, v80
	v_exp_f32_e32 v88, v88
	v_pk_add_f32 v[90:91], v[86:87], 0 op_sel_hi:[1,0]
	v_add_u32_e32 v86, 0x8000, v86
	v_pk_add_f32 v[90:91], v[84:85], v[90:91]
	v_add_u32_e32 v84, 0x8000, v84
	v_pk_add_f32 v[90:91], v[82:83], v[90:91]
	v_add_u32_e32 v82, 0x8000, v82
	v_pk_add_f32 v[90:91], v[80:81], v[90:91]
	v_add_u32_e32 v80, 0x8000, v80
	v_pk_fma_f32 v[118:119], v[118:119], v[88:89], v[90:91]
	v_max_f32_e32 v90, v128, v128
	v_max_f32_e32 v91, v130, v130
	v_max_f32_e32 v90, v91, v90
	v_max3_f32 v90, v134, v132, v90
	ds_write_b16_d16_hi v199, v86 offset:144
	ds_write_b16_d16_hi v199, v84 offset:176
	ds_write_b16_d16_hi v199, v82 offset:208
	ds_write_b16_d16_hi v199, v80 offset:240
	s_waitcnt lgkmcnt(4)
	s_nop 1
	v_max_f32_dpp v90, v90, v90 quad_perm:[1,0,3,2] row_mask:0xf bank_mask:0xf
	v_add_u32_e32 v87, 0x8000, v87
	v_add_u32_e32 v85, 0x8000, v85
	v_add_u32_e32 v83, 0x8000, v83
	v_add_u32_e32 v81, 0x8000, v81
	s_waitcnt lgkmcnt(0)
	s_nop 1
	v_max_f32_dpp v90, v90, v90 quad_perm:[2,3,0,1] row_mask:0xf bank_mask:0xf
	ds_write_b16_d16_hi v199, v87
	ds_write_b16_d16_hi v199, v85 offset:32
	ds_write_b16_d16_hi v199, v83 offset:64
	ds_write_b16_d16_hi v199, v81 offset:96
	s_waitcnt lgkmcnt(4)
	s_nop 1
	v_max_f32_dpp v90, v90, v90 row_half_mirror row_mask:0xf bank_mask:0xf
	s_nop 1
	v_mov_b32_dpp v91, v90 row_mirror row_mask:0xf bank_mask:0xf
	s_waitcnt lgkmcnt(0)
	v_max3_f32 v145, v218, v90, v91
	v_sub_f32_e32 v90, v218, v145
	v_exp_f32_e32 v147, v90
	v_max_f32_e32 v90, v129, v129
	v_max_f32_e32 v90, v92, v90
	v_max3_f32 v90, v135, v133, v90
	v_sub_f32_e32 v91, v134, v145
	v_exp_f32_e32 v143, v91
	v_sub_f32_e32 v91, v132, v145
	v_exp_f32_e32 v95, v91
	s_waitcnt lgkmcnt(0)
	s_nop 1
	v_max_f32_dpp v90, v90, v90 quad_perm:[1,0,3,2] row_mask:0xf bank_mask:0xf
	v_sub_f32_e32 v91, v130, v145
	v_exp_f32_e32 v93, v91
	v_sub_f32_e32 v91, v128, v145
	v_exp_f32_e32 v91, v91
	s_waitcnt lgkmcnt(0)
	s_nop 1
	v_max_f32_dpp v90, v90, v90 quad_perm:[2,3,0,1] row_mask:0xf bank_mask:0xf
	v_add_u32_e32 v86, 0x8000, v143
	v_add_u32_e32 v84, 0x8000, v95
	v_add_u32_e32 v82, 0x8000, v93
	v_add_u32_e32 v80, 0x8000, v91
	s_waitcnt lgkmcnt(0)
	s_nop 1
	v_max_f32_dpp v90, v90, v90 row_half_mirror row_mask:0xf bank_mask:0xf
	s_nop 1
	v_mov_b32_dpp v92, v90 row_mirror row_mask:0xf bank_mask:0xf
	ds_write_b16_d16_hi v199, v86 offset:288
	ds_write_b16_d16_hi v199, v84 offset:320
	ds_write_b16_d16_hi v199, v82 offset:352
	ds_write_b16_d16_hi v199, v80 offset:384
	s_waitcnt lgkmcnt(4)
; #define LAS __attribute__((address_space(3)))
; __device__ __forceinline__ bf16_t f2bf(float f) { return (bf16_t)((__float_as_uint(f) + 0x8000u) >> 16); }
; #define MFMA16(a, b, c) __builtin_amdgcn_mfma_f32_16x16x32_bf16(a, b, c, 0, 0, 0)
; __device__ __forceinline__ void attn_phase(const Params& p, int l, bf16_t* PROJ, LAS unsigned char* L) {
;     ...
;                 const float mn = fmaxf(mrow[jj], tm), alpha = __builtin_amdgcn_exp2f(mrow[jj] - mn); mrow[jj] = mn;
;                 float rsum = 0.f;
; #pragma unroll
;                 for (int nt = 0; nt < 4; ++nt) { const float pv = __builtin_amdgcn_exp2f(s[nt][jj] - mn); s[nt][jj] = pv; rsum += pv; }
;                 lsum[jj] = lsum[jj] * alpha + rsum;
; #pragma unroll
;                 for (int e = 0; e < 8; ++e) O[e][jj] *= alpha;
;             }
;             LAS bf16_t* Pw = Ps + wid * (16 * 72);
; #pragma unroll
;             for (int nt = 0; nt < 4; ++nt)
; #pragma unroll
;                 for (int jj = 0; jj < 4; ++jj) Pw[(fq * 4 + jj) * 72 + nt * 16 + fr] = f2bf(s[nt][jj]);
; #pragma unroll
;             for (int ks = 0; ks < 2; ++ks) { const bf16x8 a = LDFRAG(Pw, fr, 72, ks * 32 + fq * 8);
; #pragma unroll
;                 for (int e = 0; e < 8; ++e) O[e] = MFMA16(a, v_frag(Vs + hh * 16384, lane, e, ks), O[e]); }
	v_max3_f32 v128, v217, v90, v92
	v_sub_f32_e32 v90, v135, v128
	v_exp_f32_e32 v142, v90
	v_sub_f32_e32 v90, v133, v128
	v_exp_f32_e32 v94, v90
	v_sub_f32_e32 v90, v131, v128
	v_exp_f32_e32 v92, v90
	v_sub_f32_e32 v90, v129, v128
	v_exp_f32_e32 v90, v90
	v_sub_f32_e32 v130, v217, v128
	v_add_u32_e32 v86, 0x8000, v142
	v_add_u32_e32 v84, 0x8000, v94
	v_add_u32_e32 v82, 0x8000, v92
	v_add_u32_e32 v80, 0x8000, v90
	v_exp_f32_e32 v146, v130
	v_pk_add_f32 v[130:131], v[142:143], 0 op_sel_hi:[1,0]
	ds_write_b16_d16_hi v199, v86 offset:432
	ds_write_b16_d16_hi v199, v84 offset:464
	ds_write_b16_d16_hi v199, v82 offset:496
	ds_write_b16_d16_hi v199, v80 offset:528
	v_pk_add_f32 v[130:131], v[94:95], v[130:131]
	ds_read_b128 v[80:83], v160
	ds_read_b64_tr_b16 v[84:85], v200 offset:34816
	ds_read_b64_tr_b16 v[86:87], v201 offset:35840
	ds_read_b64_tr_b16 v[226:227], v202 offset:34816
	ds_read_b64_tr_b16 v[228:229], v203 offset:35840
	ds_read_b64_tr_b16 v[230:231], v204 offset:34816
	ds_read_b64_tr_b16 v[232:233], v205 offset:35840
	ds_read_b64_tr_b16 v[234:235], v206 offset:34816
	ds_read_b64_tr_b16 v[236:237], v207 offset:35840
	ds_read_b64_tr_b16 v[238:239], v208 offset:34816
	ds_read_b64_tr_b16 v[240:241], v209 offset:35840
	ds_read_b64_tr_b16 v[242:243], v210 offset:34816
	ds_read_b64_tr_b16 v[244:245], v211 offset:35840
	ds_read_b128 v[246:249], v160 offset:64
	v_pk_add_f32 v[130:131], v[92:93], v[130:131]
	v_mov_b32_e32 v132, v89
	v_pk_add_f32 v[130:131], v[90:91], v[130:131]
	v_mov_b32_e32 v133, v88
	v_pk_fma_f32 v[116:117], v[116:117], v[146:147], v[130:131]
	v_mov_b32_e32 v130, v147
	v_mov_b32_e32 v131, v146
	v_pk_mul_f32 v[18:19], v[18:19], v[130:131]
	v_pk_mul_f32 v[16:17], v[16:17], v[132:133]
	v_pk_mul_f32 v[22:23], v[22:23], v[130:131]
	v_pk_mul_f32 v[20:21], v[20:21], v[132:133]
	s_waitcnt lgkmcnt(11)
	v_mfma_f32_16x16x32_bf16 v[16:19], v[80:83], v[84:87], v[16:19]
	ds_read_b64_tr_b16 v[84:85], v212 offset:34816
	ds_read_b64_tr_b16 v[86:87], v213 offset:35840
	v_pk_mul_f32 v[26:27], v[26:27], v[130:131]
	v_pk_mul_f32 v[24:25], v[24:25], v[132:133]
	s_waitcnt lgkmcnt(11)
	v_mfma_f32_16x16x32_bf16 v[20:23], v[80:83], v[226:229], v[20:23]
	ds_read_b64_tr_b16 v[226:227], v214 offset:34816
	ds_read_b64_tr_b16 v[228:229], v215 offset:35840
	v_pk_mul_f32 v[30:31], v[30:31], v[130:131]
	v_pk_mul_f32 v[28:29], v[28:29], v[132:133]
	s_waitcnt lgkmcnt(11)
	v_mfma_f32_16x16x32_bf16 v[24:27], v[80:83], v[230:233], v[24:27]
	ds_read_b64_tr_b16 v[230:231], v200 offset:43008
	ds_read_b64_tr_b16 v[232:233], v201 offset:44032
	v_pk_mul_f32 v[34:35], v[34:35], v[130:131]
	v_pk_mul_f32 v[32:33], v[32:33], v[132:133]
	s_waitcnt lgkmcnt(11)
	v_mfma_f32_16x16x32_bf16 v[28:31], v[80:83], v[234:237], v[28:31]
	ds_read_b64_tr_b16 v[234:235], v202 offset:43008
	ds_read_b64_tr_b16 v[236:237], v203 offset:44032
	v_pk_mul_f32 v[38:39], v[38:39], v[130:131]
	v_pk_mul_f32 v[36:37], v[36:37], v[132:133]
	s_waitcnt lgkmcnt(11)
	v_mfma_f32_16x16x32_bf16 v[32:35], v[80:83], v[238:241], v[32:35]
	ds_read_b64_tr_b16 v[238:239], v204 offset:43008
	ds_read_b64_tr_b16 v[240:241], v205 offset:44032
	v_pk_mul_f32 v[42:43], v[42:43], v[130:131]
	v_pk_mul_f32 v[40:41], v[40:41], v[132:133]
	s_waitcnt lgkmcnt(11)
	v_mfma_f32_16x16x32_bf16 v[36:39], v[80:83], v[242:245], v[36:39]
	ds_read_b64_tr_b16 v[242:243], v206 offset:43008
	ds_read_b64_tr_b16 v[244:245], v207 offset:44032
	v_pk_mul_f32 v[46:47], v[46:47], v[130:131]
	v_pk_mul_f32 v[44:45], v[44:45], v[132:133]
	s_waitcnt lgkmcnt(10)
	v_mfma_f32_16x16x32_bf16 v[40:43], v[80:83], v[84:87], v[40:43]
	ds_read_b64_tr_b16 v[84:85], v208 offset:43008
	ds_read_b64_tr_b16 v[86:87], v209 offset:44032
	s_waitcnt lgkmcnt(10)
	v_mfma_f32_16x16x32_bf16 v[44:47], v[80:83], v[226:229], v[44:47]
	ds_read_b64_tr_b16 v[226:227], v210 offset:43008
	ds_read_b64_tr_b16 v[228:229], v211 offset:44032
	s_waitcnt lgkmcnt(10)
	v_mfma_f32_16x16x32_bf16 v[16:19], v[246:249], v[230:233], v[16:19]
	ds_read_b64_tr_b16 v[230:231], v212 offset:43008
	ds_read_b64_tr_b16 v[232:233], v213 offset:44032
	s_waitcnt lgkmcnt(10)
	v_mfma_f32_16x16x32_bf16 v[20:23], v[246:249], v[234:237], v[20:23]
	ds_read_b64_tr_b16 v[234:235], v214 offset:43008
	ds_read_b64_tr_b16 v[236:237], v215 offset:44032
	s_waitcnt lgkmcnt(10)
	v_mfma_f32_16x16x32_bf16 v[24:27], v[246:249], v[238:241], v[24:27]
	s_waitcnt lgkmcnt(8)
	v_mfma_f32_16x16x32_bf16 v[28:31], v[246:249], v[242:245], v[28:31]
	s_waitcnt lgkmcnt(6)
	v_mfma_f32_16x16x32_bf16 v[32:35], v[246:249], v[84:87], v[32:35]
	s_waitcnt lgkmcnt(4)
	v_mfma_f32_16x16x32_bf16 v[36:39], v[246:249], v[226:229], v[36:39]
	s_waitcnt lgkmcnt(2)
	v_mfma_f32_16x16x32_bf16 v[40:43], v[246:249], v[230:233], v[40:43]
	s_waitcnt lgkmcnt(0)
	v_mfma_f32_16x16x32_bf16 v[44:47], v[246:249], v[234:237], v[44:47]
	s_cbranch_scc1 .LBB0_335
	v_mov_b32_e32 v217, v128
	v_mov_b32_e32 v218, v145
	v_mov_b32_e32 v219, v144
	v_mov_b32_e32 v220, v221
	s_mov_b32 s3, s20
	s_branch .LBB0_348
